# also scanB chains spread over all 8 XCDs (8 workgroups per XCD) with a dense index for the NA / ctx split
# baseline (speedup 1.0000x reference)
.LBB0_689:
	v_readlane_b32 s4, v255, 7
	s_cmp_eq_u32 s4, 3
	s_cselect_b64 s[8:9], -1, 0
	v_readlane_b32 s5, v255, 8
	v_writelane_b32 v255, s8, 12
	s_cmp_lg_u32 s4, 3
	s_cselect_b64 s[86:87], -1, 0
	v_writelane_b32 v255, s9, 13
	v_readlane_b32 s8, v253, 4
	s_cmp_le_i32 s8, s2
	s_cselect_b64 s[4:5], -1, 0
	s_and_b64 s[4:5], s[4:5], s[36:37]
	s_andn2_b64 vcc, exec, s[4:5]
	v_readlane_b32 s9, v253, 5
	v_readlane_b32 s10, v253, 6
	v_readlane_b32 s11, v253, 7
	s_cbranch_vccnz .LBB0_1191
	v_writelane_b32 v255, s92, 60
	s_cmpk_lg_i32 s77, 0x100
	s_mov_b64 s[36:37], -1
	s_cbranch_scc0 .LBB0_858
	s_mov_b64 s[62:63], s[74:75]
	s_mov_b32 s52, s92
	s_mov_b32 s68, s93
	s_mov_b32 s10, s77
	s_cmp_gt_i32 s52, 63
	v_mbcnt_lo_u32_b32 v0, -1, 0
	v_mbcnt_hi_u32_b32 v0, -1, v0
	s_cbranch_scc1 .LBB0_712
	s_lshl_b32 s2, s68, 6
	s_waitcnt lgkmcnt(0)
	v_lshlrev_b32_e32 v1, 2, v0
	s_add_i32 s4, 0, 0x12000
	v_and_b32_e32 v1, 16, v1
	s_cmp_lt_i32 s68, 4
	v_and_or_b32 v3, v0, 3, v1
	v_lshlrev_b32_e32 v1, 4, v0
	s_cselect_b64 s[38:39], -1, 0
	s_cmp_gt_i32 s68, 1
	v_lshrrev_b32_e32 v2, 1, v0
	v_add_u32_e32 v199, s4, v1
	s_cselect_b64 s[40:41], -1, 0
	s_add_i32 s4, s68, -2
	v_and_b32_e32 v2, 12, v2
	s_lshl_b32 s5, s4, 5
	v_add_u32_e32 v198, 0, v1
	v_ashrrev_i32_e32 v1, 31, v0
	v_or3_b32 v200, v2, v3, s5
	s_add_u32 s5, s62, 0x3b400000
	v_ashrrev_i32_e32 v196, 5, v0
	s_addc_u32 s6, s63, 0
	v_lshl_add_u64 v[0:1], v[0:1], 4, s[62:63]
	s_add_i32 s42, s2, 0xffffff00
	s_mov_b32 s43, s25
	v_lshl_add_u64 v[0:1], s[42:43], 4, v[0:1]
	s_mov_b64 s[12:13], 0x45700000
	v_sub_u32_e32 v197, 1, v196
	s_lshl_b32 s8, s4, 11
	s_lshl_b32 s9, s68, 12
	v_lshl_add_u64 v[192:193], v[0:1], 0, s[12:13]
	v_lshl_add_u32 v201, s42, 4, v198
	v_lshl_add_u32 v202, s68, 10, v198
	s_mov_b32 s11, s52
	s_branch .LBB0_694

.LBB0_858:
	s_and_b64 vcc, exec, s[36:37]
	s_cbranch_vccz .LBB0_1173
	s_lshr_b32 s4, s92, 5
	s_and_b32 s5, s92, 31
	s_cmp_lt_u32 s5, 8
	s_cbranch_scc1 .Lxs_chain
	s_mul_i32 s4, s4, 24
	s_add_i32 s92, s4, s5
	s_add_i32 s92, s92, 56
	s_branch .Lxs_done
.Lxs_chain:
	s_lshl_b32 s4, s4, 3
	s_add_i32 s92, s4, s5
.Lxs_done:
	s_cmp_gt_i32 s92, 63
	s_mov_b64 s[36:37], -1
	s_cbranch_scc0 .LBB0_1150
	v_readlane_b32 s4, v255, 7
	s_lshl_b32 s10, s4, 3
	s_cmpk_gt_u32 s92, 0x7f
	v_readlane_b32 s5, v255, 8
	s_cbranch_scc0 .LBB0_1005
	v_readlane_b32 s4, v253, 0
	v_readlane_b32 s5, v253, 1
	s_mov_b32 s68, s93
	s_movk_i32 s77, 0x100
	s_mov_b64 s[62:63], s[74:75]
	s_mov_b32 s69, s92
	s_load_dwordx2 s[4:5], s[4:5], 0x48
	s_waitcnt lgkmcnt(0)
	s_waitcnt vmcnt(0)
	v_mbcnt_lo_u32_b32 v2, -1, 0
	v_mbcnt_hi_u32_b32 v2, -1, v2
	s_mov_b64 s[8:9], 0x43800000
	v_ashrrev_i32_e32 v3, 4, v2
	s_waitcnt vmcnt(8)
	v_lshlrev_b32_e32 v134, 3, v3
	v_ashrrev_i32_e32 v135, 31, v134
	v_lshlrev_b32_e32 v0, 1, v2
	s_waitcnt lgkmcnt(0)
	v_and_b32_e32 v1, 3, v2
	v_and_or_b32 v133, v0, 24, v1
	v_lshl_add_u64 v[0:1], v[134:135], 1, s[62:63]
	v_lshl_add_u64 v[136:137], v[0:1], 0, s[8:9]
	s_mov_b32 s8, 0x84210843
	v_mul_hi_i32 v0, v2, s8
	v_add_u32_e32 v0, v0, v2
	v_lshrrev_b32_e32 v1, 31, v0
	v_ashrrev_i32_e32 v0, 4, v0
	s_waitcnt vmcnt(3)
	v_add_u32_e32 v154, v0, v1
	s_add_u32 s58, s62, 0x21400000
	v_mul_lo_u32 v0, v154, 31
	s_addc_u32 s59, s63, 0
	s_lshl_b32 s2, s68, 10
	v_sub_u32_e32 v0, v2, v0
	s_add_i32 s2, s2, 0
	v_ashrrev_i32_e32 v1, 31, v0
	s_add_i32 s2, s2, 0x1a000
	v_lshl_add_u64 v[140:141], v[0:1], 2, s[4:5]
	v_lshlrev_b32_e32 v1, 7, v154
	v_lshlrev_b32_e32 v0, 2, v0
	v_add3_u32 v155, s2, v1, v0
	v_add_u32_e32 v0, 64, v2
	v_mul_hi_i32 v1, v0, s8
	v_add_u32_e32 v1, v1, v0
	v_lshlrev_b32_e32 v138, 2, v3
	v_lshrrev_b32_e32 v3, 31, v1
	v_ashrrev_i32_e32 v1, 4, v1
	s_waitcnt vmcnt(2)
	v_add_u32_e32 v156, v1, v3
	v_mul_lo_u32 v1, v156, 31
	v_sub_u32_e32 v0, v0, v1
	v_ashrrev_i32_e32 v1, 31, v0
	v_lshl_add_u64 v[142:143], v[0:1], 2, s[4:5]
	v_lshlrev_b32_e32 v1, 7, v156
	v_lshlrev_b32_e32 v0, 2, v0
	v_add3_u32 v157, s2, v1, v0
	v_add_u32_e32 v0, 0x80, v2
	v_mul_hi_i32 v1, v0, s8
	v_add_u32_e32 v1, v1, v0
	v_lshrrev_b32_e32 v3, 31, v1
	v_ashrrev_i32_e32 v1, 4, v1
	v_add_u32_e32 v158, v1, v3
	v_mul_lo_u32 v1, v158, 31
	v_sub_u32_e32 v0, v0, v1
	v_ashrrev_i32_e32 v1, 31, v0
	v_lshl_add_u64 v[144:145], v[0:1], 2, s[4:5]
	v_lshlrev_b32_e32 v1, 7, v158
	v_lshlrev_b32_e32 v0, 2, v0
	s_movk_i32 s6, 0xf8
	v_add3_u32 v159, s2, v1, v0
	v_add_u32_e32 v0, 0xc0, v2
	v_cmp_gt_i32_e64 s[36:37], s6, v2
	s_movk_i32 s6, 0xb8
	v_mul_hi_i32 v1, v0, s8
	v_cmp_gt_i32_e64 s[38:39], s6, v2
	s_movk_i32 s6, 0x78
	v_add_u32_e32 v1, v1, v0
	v_and_b32_e32 v132, 15, v2
	v_cmp_gt_i32_e64 s[40:41], s6, v2
	v_cmp_gt_i32_e64 s[42:43], 56, v2
	v_lshrrev_b32_e32 v2, 31, v1
	v_ashrrev_i32_e32 v1, 4, v1
	s_waitcnt vmcnt(1)
	v_add_u32_e32 v160, v1, v2
	v_mul_lo_u32 v1, v160, 31
	v_sub_u32_e32 v0, v0, v1
	v_ashrrev_i32_e32 v1, 31, v0
	v_lshl_add_u64 v[146:147], v[0:1], 2, s[4:5]
	s_and_b32 s4, s68, 3
	s_cmp_eq_u32 s4, 2
	s_cselect_b32 s5, 24, 32
	s_add_u32 s60, s62, 0x2ed00000
	s_mul_i32 s6, s92, 40
	v_lshlrev_b32_e32 v1, 7, v160
	v_lshlrev_b32_e32 v0, 2, v0
	v_lshl_or_b32 v162, s4, 4, v132
	s_addc_u32 s61, s63, 0
	s_add_i32 s6, s68, s6
	v_ashrrev_i32_e32 v139, 31, v138
	v_add3_u32 v161, s2, v1, v0
	v_med3_u32 v163, v162, 8, 56
	s_waitcnt vmcnt(0)
	v_or_b32_e32 v164, 0x4000, v133
	v_or_b32_e32 v165, 0x4020, v133
	v_or_b32_e32 v166, 0x4040, v133
	v_or_b32_e32 v167, 0x4060, v133
	v_or_b32_e32 v168, 0x4080, v133
	v_or_b32_e32 v169, 0x40a0, v133
	v_or_b32_e32 v170, 0x40c0, v133
	v_or_b32_e32 v171, 0x40e0, v133
	s_addk_i32 s6, 0xf800
	s_mov_b32 s8, 0
	s_branch .LBB0_863

.LBB0_1154:
	s_mov_b64 s[36:37], -1
	s_and_b64 vcc, exec, s[38:39]
	s_cbranch_vccz .LBB0_1168
	s_and_b64 vcc, exec, s[40:41]
	s_cbranch_vccz .LBB0_1163
	s_bfe_u32 s27, s10, 0x10004
	s_ashr_i32 s12, s10, 5
	s_mul_i32 s11, s27, 0x4200000
	s_add_u32 s11, s5, s11
	s_addc_u32 s13, s6, 0
	s_lshl_b32 s24, s10, 8
	s_and_b32 s24, s24, 0xf00
	s_add_u32 s44, s11, s24
	s_addc_u32 s45, s13, 0
	s_lshl_b32 s11, s12, 13
	s_lshl_b32 s12, s12, 8
	s_addk_i32 s12, 0x4000
	s_lshl_b32 s13, s27, 2
	s_cmp_eq_u32 s27, 0
	s_cselect_b64 s[36:37], -1, 0
	s_waitcnt vmcnt(41)
	v_cndmask_b32_e64 v0, v197, v196, s[36:37]
	v_lshl_add_u32 v208, v0, 12, v200
	s_waitcnt lgkmcnt(0)
	s_barrier
	s_waitcnt lgkmcnt(0)
	s_waitcnt vmcnt(37)
	v_lshl_add_u64 v[16:17], v[208:209], 2, s[44:45]
	s_and_b64 s[44:45], s[36:37], exec
	s_mov_b32 s24, 0
	s_cselect_b32 s27, 1, -1
	s_cselect_b32 s33, 2, -2
	s_cselect_b32 s43, 3, -3
	s_cselect_b32 s46, 8, -8
	s_cselect_b32 s47, 9, -9
	s_cselect_b32 s48, 10, -10
	s_cselect_b32 s49, 11, -11
	s_cselect_b32 s50, 16, -16
	s_cselect_b32 s51, 17, 0xffffffef
	s_cselect_b32 s52, 18, 0xffffffee
	s_cselect_b32 s53, 19, 0xffffffed
	s_cselect_b32 s54, 24, 0xffffffe8
	s_cselect_b32 s55, 25, 0xffffffe7
	s_cselect_b32 s56, 26, 0xffffffe6
	s_cselect_b32 s57, 27, 0xffffffe5
	s_movk_i32 s58, 0x20ff
	s_mov_b32 s59, 0
	s_mov_b32 s60, 0
	s_mov_b32 s61, 0
	v_mbcnt_lo_u32_b32 v210, -1, 0
	v_mbcnt_hi_u32_b32 v210, -1, v210
	v_and_b32_e32 v210, 3, v210
	s_lshl_b32 s62, s27, 12
	s_add_i32 s62, s62, -4
	v_mul_lo_u32 v210, v210, s62
	v_ashrrev_i32_e32 v211, 31, v210
	v_lshl_add_u64 v[216:217], v[16:17], 0, v[210:211]
	s_barrier
	s_waitcnt vmcnt(0)
	s_branch .LBB0_1158
.LBB0_1157:
	s_add_i32 s45, s61, 1
	s_cmp_lg_u32 s61, 2
	s_cselect_b32 s61, s45, 0
	s_sub_i32 s44, s44, s13
	s_add_i32 s44, s44, s62
	s_mov_b32 vcc_lo, 0xaaaaaaaa
	s_mov_b32 vcc_hi, 0xaaaaaaaa
	s_nop 7
	v_mov_b32_dpp v210, v0 quad_perm:[1,0,3,2] row_mask:0xf bank_mask:0xf
	v_mov_b32_dpp v211, v1 quad_perm:[1,0,3,2] row_mask:0xf bank_mask:0xf
	v_cndmask_b32_e32 v0, v0, v211, vcc
	v_cndmask_b32_e32 v1, v210, v1, vcc
	v_mov_b32_dpp v212, v2 quad_perm:[1,0,3,2] row_mask:0xf bank_mask:0xf
	v_mov_b32_dpp v213, v3 quad_perm:[1,0,3,2] row_mask:0xf bank_mask:0xf
	v_cndmask_b32_e32 v2, v2, v213, vcc
	v_cndmask_b32_e32 v3, v212, v3, vcc
	v_mov_b32_dpp v210, v4 quad_perm:[1,0,3,2] row_mask:0xf bank_mask:0xf
	v_mov_b32_dpp v211, v5 quad_perm:[1,0,3,2] row_mask:0xf bank_mask:0xf
	v_cndmask_b32_e32 v4, v4, v211, vcc
	v_cndmask_b32_e32 v5, v210, v5, vcc
	v_mov_b32_dpp v212, v6 quad_perm:[1,0,3,2] row_mask:0xf bank_mask:0xf
	v_mov_b32_dpp v213, v7 quad_perm:[1,0,3,2] row_mask:0xf bank_mask:0xf
	v_cndmask_b32_e32 v6, v6, v213, vcc
	v_cndmask_b32_e32 v7, v212, v7, vcc
	v_mov_b32_dpp v210, v8 quad_perm:[1,0,3,2] row_mask:0xf bank_mask:0xf
	v_mov_b32_dpp v211, v9 quad_perm:[1,0,3,2] row_mask:0xf bank_mask:0xf
	v_cndmask_b32_e32 v8, v8, v211, vcc
	v_cndmask_b32_e32 v9, v210, v9, vcc
	v_mov_b32_dpp v212, v10 quad_perm:[1,0,3,2] row_mask:0xf bank_mask:0xf
	v_mov_b32_dpp v213, v11 quad_perm:[1,0,3,2] row_mask:0xf bank_mask:0xf
	v_cndmask_b32_e32 v10, v10, v213, vcc
	v_cndmask_b32_e32 v11, v212, v11, vcc
	v_mov_b32_dpp v210, v12 quad_perm:[1,0,3,2] row_mask:0xf bank_mask:0xf
	v_mov_b32_dpp v211, v13 quad_perm:[1,0,3,2] row_mask:0xf bank_mask:0xf
	v_cndmask_b32_e32 v12, v12, v211, vcc
	v_cndmask_b32_e32 v13, v210, v13, vcc
	v_mov_b32_dpp v212, v14 quad_perm:[1,0,3,2] row_mask:0xf bank_mask:0xf
	v_mov_b32_dpp v213, v15 quad_perm:[1,0,3,2] row_mask:0xf bank_mask:0xf
	v_cndmask_b32_e32 v14, v14, v213, vcc
	v_cndmask_b32_e32 v15, v212, v15, vcc
	s_mov_b32 vcc_lo, 0xcccccccc
	s_mov_b32 vcc_hi, 0xcccccccc
	v_mov_b32_dpp v210, v0 quad_perm:[2,3,0,1] row_mask:0xf bank_mask:0xf
	v_mov_b32_dpp v211, v2 quad_perm:[2,3,0,1] row_mask:0xf bank_mask:0xf
	v_cndmask_b32_e32 v0, v0, v211, vcc
	v_cndmask_b32_e32 v2, v210, v2, vcc
	v_mov_b32_dpp v212, v1 quad_perm:[2,3,0,1] row_mask:0xf bank_mask:0xf
	v_mov_b32_dpp v213, v3 quad_perm:[2,3,0,1] row_mask:0xf bank_mask:0xf
	v_cndmask_b32_e32 v1, v1, v213, vcc
	v_cndmask_b32_e32 v3, v212, v3, vcc
	v_mov_b32_dpp v210, v4 quad_perm:[2,3,0,1] row_mask:0xf bank_mask:0xf
	v_mov_b32_dpp v211, v6 quad_perm:[2,3,0,1] row_mask:0xf bank_mask:0xf
	v_cndmask_b32_e32 v4, v4, v211, vcc
	v_cndmask_b32_e32 v6, v210, v6, vcc
	v_mov_b32_dpp v212, v5 quad_perm:[2,3,0,1] row_mask:0xf bank_mask:0xf
	v_mov_b32_dpp v213, v7 quad_perm:[2,3,0,1] row_mask:0xf bank_mask:0xf
	v_cndmask_b32_e32 v5, v5, v213, vcc
	v_cndmask_b32_e32 v7, v212, v7, vcc
	v_mov_b32_dpp v210, v8 quad_perm:[2,3,0,1] row_mask:0xf bank_mask:0xf
	v_mov_b32_dpp v211, v10 quad_perm:[2,3,0,1] row_mask:0xf bank_mask:0xf
	v_cndmask_b32_e32 v8, v8, v211, vcc
	v_cndmask_b32_e32 v10, v210, v10, vcc
	v_mov_b32_dpp v212, v9 quad_perm:[2,3,0,1] row_mask:0xf bank_mask:0xf
	v_mov_b32_dpp v213, v11 quad_perm:[2,3,0,1] row_mask:0xf bank_mask:0xf
	v_cndmask_b32_e32 v9, v9, v213, vcc
	v_cndmask_b32_e32 v11, v212, v11, vcc
	v_mov_b32_dpp v210, v12 quad_perm:[2,3,0,1] row_mask:0xf bank_mask:0xf
	v_mov_b32_dpp v211, v14 quad_perm:[2,3,0,1] row_mask:0xf bank_mask:0xf
	v_cndmask_b32_e32 v12, v12, v211, vcc
	v_cndmask_b32_e32 v14, v210, v14, vcc
	v_mov_b32_dpp v212, v13 quad_perm:[2,3,0,1] row_mask:0xf bank_mask:0xf
	v_mov_b32_dpp v213, v15 quad_perm:[2,3,0,1] row_mask:0xf bank_mask:0xf
	v_cndmask_b32_e32 v13, v13, v213, vcc
	v_cndmask_b32_e32 v15, v212, v15, vcc
	s_mov_b32 s62, s44
	s_ashr_i32 s63, s62, 31
	s_lshl_b64 s[62:63], s[62:63], 12
	v_lshl_add_u64 v[214:215], v[216:217], 0, s[62:63]
	global_store_dwordx4 v[214:215], v[0:3], off
	s_add_i32 s62, s44, s46
	s_ashr_i32 s63, s62, 31
	s_lshl_b64 s[62:63], s[62:63], 12
	v_lshl_add_u64 v[214:215], v[216:217], 0, s[62:63]
	global_store_dwordx4 v[214:215], v[4:7], off
	s_add_i32 s62, s44, s50
	s_ashr_i32 s63, s62, 31
	s_lshl_b64 s[62:63], s[62:63], 12
	v_lshl_add_u64 v[214:215], v[216:217], 0, s[62:63]
	global_store_dwordx4 v[214:215], v[8:11], off
	s_add_i32 s62, s44, s54
	s_ashr_i32 s63, s62, 31
	s_lshl_b64 s[62:63], s[62:63], 12
	v_lshl_add_u64 v[214:215], v[216:217], 0, s[62:63]
	global_store_dwordx4 v[214:215], v[12:15], off
	s_waitcnt lgkmcnt(0)
	s_add_i32 s60, s60, 1
	s_sub_i32 s58, s58, 32
	s_add_i32 s59, s59, 32
	s_add_i32 s24, s24, 2
	s_cmp_lg_u32 s58, -1
	s_barrier
	s_cbranch_scc0 .LBB0_1162

.LBB0_1190:
	s_mov_b64 s[74:75], s[62:63]
	s_mov_b32 s92, s69
	v_readlane_b32 s92, v255, 60
	s_mov_b32 s93, s68
